# per-tile accumulator clear: once instead of twice, and as 64 v_mov_b64 instead of 128 v_mov_b32 (K-loop 8-byte phases preserved) + EpiResid prefetch
# speedup vs baseline: 1.0171x; 1.0004x over previous
; template <class Epi, class Sched, bool ALIGN_EPI = false, bool SP2 = false>
; __device__ __forceinline__ void gemm_phase(PG8_LAS unsigned char* lds, const Gemm g, const Sched& S, const Epi& E, int tid_in) {
;     ...
;         for (int t = 0; t < nt; t += 2) {
;             const bool last = (t == nt - 2);
;             const char* a1 = cA + (size_t)(t + 1) * kstep;
;             const char* a2 = last ? nA : cA + (size_t)(t + 2) * kstep; const char* b2 = last ? nB : cB + (size_t)(t + 2) * kstep;
;             const char* a3 = a2 + kstep; const char* b3 = b2 + kstep;
;     ...
; #pragma unroll
;         for (int a = 0; a < 2; ++a)
; #pragma unroll
;             for (int b = 0; b < 2; ++b)
; #pragma unroll
;                 for (int m = 0; m < 4; ++m)
; #pragma unroll
;                     for (int n = 0; n < 2; ++n) acc[a][b][m][n] = (f32x4){0.f, 0.f, 0.f, 0.f};
.Lkeep_acc_1:
	s_add_u32 s38, s38, 0x80
	s_addc_u32 s39, s39, 0
	s_add_u32 s81, s40, 0x100
	s_addc_u32 s83, s41, 0
	s_mov_b32 s40, 0
	v_mov_b64_e32 v[0:1], 0
	v_mov_b64_e32 v[2:3], 0
	v_mov_b64_e32 v[4:5], 0
	v_mov_b64_e32 v[6:7], 0
	v_mov_b64_e32 v[8:9], 0
	v_mov_b64_e32 v[10:11], 0
	v_mov_b64_e32 v[12:13], 0
	v_mov_b64_e32 v[14:15], 0
	v_mov_b64_e32 v[16:17], 0
	v_mov_b64_e32 v[18:19], 0
	v_mov_b64_e32 v[20:21], 0
	v_mov_b64_e32 v[22:23], 0
	v_mov_b64_e32 v[24:25], 0
	v_mov_b64_e32 v[26:27], 0
	v_mov_b64_e32 v[28:29], 0
	v_mov_b64_e32 v[30:31], 0
	v_mov_b64_e32 v[32:33], 0
	v_mov_b64_e32 v[34:35], 0
	v_mov_b64_e32 v[36:37], 0
	v_mov_b64_e32 v[38:39], 0
	v_mov_b64_e32 v[40:41], 0
	v_mov_b64_e32 v[42:43], 0
	v_mov_b64_e32 v[44:45], 0
	v_mov_b64_e32 v[46:47], 0
	v_mov_b64_e32 v[48:49], 0
	v_mov_b64_e32 v[50:51], 0
	v_mov_b64_e32 v[52:53], 0
	v_mov_b64_e32 v[54:55], 0
	v_mov_b64_e32 v[56:57], 0
	v_mov_b64_e32 v[58:59], 0
	v_mov_b64_e32 v[60:61], 0
	v_mov_b64_e32 v[62:63], 0
	v_mov_b64_e32 v[64:65], 0
	v_mov_b64_e32 v[66:67], 0
	v_mov_b64_e32 v[68:69], 0
	v_mov_b64_e32 v[70:71], 0
	v_mov_b64_e32 v[72:73], 0
	v_mov_b64_e32 v[74:75], 0
	v_mov_b64_e32 v[76:77], 0
	v_mov_b64_e32 v[78:79], 0
	v_mov_b64_e32 v[80:81], 0
	v_mov_b64_e32 v[82:83], 0
	v_mov_b64_e32 v[84:85], 0
	v_mov_b64_e32 v[86:87], 0
	v_mov_b64_e32 v[88:89], 0
	v_mov_b64_e32 v[90:91], 0
	v_mov_b64_e32 v[92:93], 0
	v_mov_b64_e32 v[94:95], 0
	v_mov_b64_e32 v[96:97], 0
	v_mov_b64_e32 v[98:99], 0
	v_mov_b64_e32 v[100:101], 0
	v_mov_b64_e32 v[102:103], 0
	v_mov_b64_e32 v[104:105], 0
	v_mov_b64_e32 v[106:107], 0
	v_mov_b64_e32 v[108:109], 0
	v_mov_b64_e32 v[110:111], 0
	v_mov_b64_e32 v[112:113], 0
	v_mov_b64_e32 v[114:115], 0
	v_mov_b64_e32 v[116:117], 0
	v_mov_b64_e32 v[118:119], 0
	v_mov_b64_e32 v[120:121], 0
	v_mov_b64_e32 v[122:123], 0
	v_mov_b64_e32 v[124:125], 0
	v_mov_b64_e32 v[126:127], 0

; template <class Epi, class Sched, bool ALIGN_EPI = false, bool SP2 = false>
; __device__ __forceinline__ void gemm_phase(PG8_LAS unsigned char* lds, const Gemm g, const Sched& S, const Epi& E, int tid_in) {
;     ...
;         for (int t = 0; t < nt; t += 2) {
;             const bool last = (t == nt - 2);
;             const char* a1 = cA + (size_t)(t + 1) * kstep;
;             const char* a2 = last ? nA : cA + (size_t)(t + 2) * kstep; const char* b2 = last ? nB : cB + (size_t)(t + 2) * kstep;
;             const char* a3 = a2 + kstep; const char* b3 = b2 + kstep;
;     ...
; #pragma unroll
;         for (int a = 0; a < 2; ++a)
; #pragma unroll
;             for (int b = 0; b < 2; ++b)
; #pragma unroll
;                 for (int m = 0; m < 4; ++m)
; #pragma unroll
;                     for (int n = 0; n < 2; ++n) acc[a][b][m][n] = (f32x4){0.f, 0.f, 0.f, 0.f};
.Lkeep_acc_2:
	s_add_u32 s4, s8, 0x80
	s_addc_u32 s5, s9, 0
	s_add_u32 s8, s6, 0x100
	s_addc_u32 s9, s7, 0
	s_mov_b32 s6, 0
	v_mov_b64_e32 v[0:1], 0
	v_mov_b64_e32 v[2:3], 0
	v_mov_b64_e32 v[4:5], 0
	v_mov_b64_e32 v[6:7], 0
	v_mov_b64_e32 v[8:9], 0
	v_mov_b64_e32 v[10:11], 0
	v_mov_b64_e32 v[12:13], 0
	v_mov_b64_e32 v[14:15], 0
	v_mov_b64_e32 v[16:17], 0
	v_mov_b64_e32 v[18:19], 0
	v_mov_b64_e32 v[20:21], 0
	v_mov_b64_e32 v[22:23], 0
	v_mov_b64_e32 v[24:25], 0
	v_mov_b64_e32 v[26:27], 0
	v_mov_b64_e32 v[28:29], 0
	v_mov_b64_e32 v[30:31], 0
	v_mov_b64_e32 v[32:33], 0
	v_mov_b64_e32 v[34:35], 0
	v_mov_b64_e32 v[36:37], 0
	v_mov_b64_e32 v[38:39], 0
	v_mov_b64_e32 v[40:41], 0
	v_mov_b64_e32 v[42:43], 0
	v_mov_b64_e32 v[44:45], 0
	v_mov_b64_e32 v[46:47], 0
	v_mov_b64_e32 v[48:49], 0
	v_mov_b64_e32 v[50:51], 0
	v_mov_b64_e32 v[52:53], 0
	v_mov_b64_e32 v[54:55], 0
	v_mov_b64_e32 v[56:57], 0
	v_mov_b64_e32 v[58:59], 0
	v_mov_b64_e32 v[60:61], 0
	v_mov_b64_e32 v[62:63], 0
	v_mov_b64_e32 v[64:65], 0
	v_mov_b64_e32 v[66:67], 0
	v_mov_b64_e32 v[68:69], 0
	v_mov_b64_e32 v[70:71], 0
	v_mov_b64_e32 v[72:73], 0
	v_mov_b64_e32 v[74:75], 0
	v_mov_b64_e32 v[76:77], 0
	v_mov_b64_e32 v[78:79], 0
	v_mov_b64_e32 v[80:81], 0
	v_mov_b64_e32 v[82:83], 0
	v_mov_b64_e32 v[84:85], 0
	v_mov_b64_e32 v[86:87], 0
	v_mov_b64_e32 v[88:89], 0
	v_mov_b64_e32 v[90:91], 0
	v_mov_b64_e32 v[92:93], 0
	v_mov_b64_e32 v[94:95], 0
	v_mov_b64_e32 v[96:97], 0
	v_mov_b64_e32 v[98:99], 0
	v_mov_b64_e32 v[100:101], 0
	v_mov_b64_e32 v[102:103], 0
	v_mov_b64_e32 v[104:105], 0
	v_mov_b64_e32 v[106:107], 0
	v_mov_b64_e32 v[108:109], 0
	v_mov_b64_e32 v[110:111], 0
	v_mov_b64_e32 v[112:113], 0
	v_mov_b64_e32 v[114:115], 0
	v_mov_b64_e32 v[116:117], 0
	v_mov_b64_e32 v[118:119], 0
	v_mov_b64_e32 v[120:121], 0
	v_mov_b64_e32 v[122:123], 0
	v_mov_b64_e32 v[124:125], 0
	v_mov_b64_e32 v[126:127], 0

; template <class Epi, class Sched, bool ALIGN_EPI = false, bool SP2 = false>
; __device__ __forceinline__ void gemm_phase(PG8_LAS unsigned char* lds, const Gemm g, const Sched& S, const Epi& E, int tid_in) {
;     ...
;         for (int t = 0; t < nt; t += 2) {
;             const bool last = (t == nt - 2);
;             const char* a1 = cA + (size_t)(t + 1) * kstep;
;             const char* a2 = last ? nA : cA + (size_t)(t + 2) * kstep; const char* b2 = last ? nB : cB + (size_t)(t + 2) * kstep;
;             const char* a3 = a2 + kstep; const char* b3 = b2 + kstep;
;     ...
; #pragma unroll
;         for (int a = 0; a < 2; ++a)
; #pragma unroll
;             for (int b = 0; b < 2; ++b)
; #pragma unroll
;                 for (int m = 0; m < 4; ++m)
; #pragma unroll
;                     for (int n = 0; n < 2; ++n) acc[a][b][m][n] = (f32x4){0.f, 0.f, 0.f, 0.f};
.Lkeep_acc_3:
	s_add_u32 s4, s40, 0x80
	s_addc_u32 s5, s41, 0
	s_add_u32 s42, s42, 0x100
	s_addc_u32 s43, s43, 0
	s_mov_b32 s40, 0
	v_mov_b64_e32 v[0:1], 0
	v_mov_b64_e32 v[2:3], 0
	v_mov_b64_e32 v[4:5], 0
	v_mov_b64_e32 v[6:7], 0
	v_mov_b64_e32 v[8:9], 0
	v_mov_b64_e32 v[10:11], 0
	v_mov_b64_e32 v[12:13], 0
	v_mov_b64_e32 v[14:15], 0
	v_mov_b64_e32 v[16:17], 0
	v_mov_b64_e32 v[18:19], 0
	v_mov_b64_e32 v[20:21], 0
	v_mov_b64_e32 v[22:23], 0
	v_mov_b64_e32 v[24:25], 0
	v_mov_b64_e32 v[26:27], 0
	v_mov_b64_e32 v[28:29], 0
	v_mov_b64_e32 v[30:31], 0
	v_mov_b64_e32 v[32:33], 0
	v_mov_b64_e32 v[34:35], 0
	v_mov_b64_e32 v[36:37], 0
	v_mov_b64_e32 v[38:39], 0
	v_mov_b64_e32 v[40:41], 0
	v_mov_b64_e32 v[42:43], 0
	v_mov_b64_e32 v[44:45], 0
	v_mov_b64_e32 v[46:47], 0
	v_mov_b64_e32 v[48:49], 0
	v_mov_b64_e32 v[50:51], 0
	v_mov_b64_e32 v[52:53], 0
	v_mov_b64_e32 v[54:55], 0
	v_mov_b64_e32 v[56:57], 0
	v_mov_b64_e32 v[58:59], 0
	v_mov_b64_e32 v[60:61], 0
	v_mov_b64_e32 v[62:63], 0
	v_mov_b64_e32 v[64:65], 0
	v_mov_b64_e32 v[66:67], 0
	v_mov_b64_e32 v[68:69], 0
	v_mov_b64_e32 v[70:71], 0
	v_mov_b64_e32 v[72:73], 0
	v_mov_b64_e32 v[74:75], 0
	v_mov_b64_e32 v[76:77], 0
	v_mov_b64_e32 v[78:79], 0
	v_mov_b64_e32 v[80:81], 0
	v_mov_b64_e32 v[82:83], 0
	v_mov_b64_e32 v[84:85], 0
	v_mov_b64_e32 v[86:87], 0
	v_mov_b64_e32 v[88:89], 0
	v_mov_b64_e32 v[90:91], 0
	v_mov_b64_e32 v[92:93], 0
	v_mov_b64_e32 v[94:95], 0
	v_mov_b64_e32 v[100:101], 0
	v_mov_b64_e32 v[102:103], 0
	v_mov_b64_e32 v[108:109], 0
	v_mov_b64_e32 v[110:111], 0
	v_mov_b64_e32 v[112:113], 0
	v_mov_b64_e32 v[114:115], 0
	v_mov_b64_e32 v[116:117], 0
	v_mov_b64_e32 v[118:119], 0
	v_mov_b64_e32 v[120:121], 0
	v_mov_b64_e32 v[122:123], 0
	v_mov_b64_e32 v[124:125], 0
	v_mov_b64_e32 v[126:127], 0
	v_mov_b64_e32 v[128:129], 0
	v_mov_b64_e32 v[130:131], 0
	v_mov_b64_e32 v[132:133], 0
	v_mov_b64_e32 v[134:135], 0

; template <class Epi, class Sched, bool ALIGN_EPI = false, bool SP2 = false>
; __device__ __forceinline__ void gemm_phase(PG8_LAS unsigned char* lds, const Gemm g, const Sched& S, const Epi& E, int tid_in) {
;     ...
;         for (int t = 0; t < nt; t += 2) {
;             const bool last = (t == nt - 2);
;             const char* a1 = cA + (size_t)(t + 1) * kstep;
;             const char* a2 = last ? nA : cA + (size_t)(t + 2) * kstep; const char* b2 = last ? nB : cB + (size_t)(t + 2) * kstep;
;             const char* a3 = a2 + kstep; const char* b3 = b2 + kstep;
;     ...
; #pragma unroll
;         for (int a = 0; a < 2; ++a)
; #pragma unroll
;             for (int b = 0; b < 2; ++b)
; #pragma unroll
;                 for (int m = 0; m < 4; ++m)
; #pragma unroll
;                     for (int n = 0; n < 2; ++n) acc[a][b][m][n] = (f32x4){0.f, 0.f, 0.f, 0.f};
.Lkeep_acc_4:
	s_add_u32 s36, s36, 0x80
	s_addc_u32 s37, s37, 0
	s_add_u32 s33, s38, 0x100
	s_addc_u32 s79, s39, 0
	s_mov_b32 s38, 0
	v_mov_b64_e32 v[0:1], 0
	v_mov_b64_e32 v[2:3], 0
	v_mov_b64_e32 v[4:5], 0
	v_mov_b64_e32 v[6:7], 0
	v_mov_b64_e32 v[8:9], 0
	v_mov_b64_e32 v[10:11], 0
	v_mov_b64_e32 v[12:13], 0
	v_mov_b64_e32 v[14:15], 0
	v_mov_b64_e32 v[16:17], 0
	v_mov_b64_e32 v[18:19], 0
	v_mov_b64_e32 v[20:21], 0
	v_mov_b64_e32 v[22:23], 0
	v_mov_b64_e32 v[24:25], 0
	v_mov_b64_e32 v[26:27], 0
	v_mov_b64_e32 v[28:29], 0
	v_mov_b64_e32 v[30:31], 0
	v_mov_b64_e32 v[32:33], 0
	v_mov_b64_e32 v[34:35], 0
	v_mov_b64_e32 v[36:37], 0
	v_mov_b64_e32 v[38:39], 0
	v_mov_b64_e32 v[40:41], 0
	v_mov_b64_e32 v[42:43], 0
	v_mov_b64_e32 v[44:45], 0
	v_mov_b64_e32 v[46:47], 0
	v_mov_b64_e32 v[48:49], 0
	v_mov_b64_e32 v[50:51], 0
	v_mov_b64_e32 v[52:53], 0
	v_mov_b64_e32 v[54:55], 0
	v_mov_b64_e32 v[56:57], 0
	v_mov_b64_e32 v[58:59], 0
	v_mov_b64_e32 v[60:61], 0
	v_mov_b64_e32 v[62:63], 0
	v_mov_b64_e32 v[64:65], 0
	v_mov_b64_e32 v[66:67], 0
	v_mov_b64_e32 v[68:69], 0
	v_mov_b64_e32 v[70:71], 0
	v_mov_b64_e32 v[72:73], 0
	v_mov_b64_e32 v[74:75], 0
	v_mov_b64_e32 v[76:77], 0
	v_mov_b64_e32 v[78:79], 0
	v_mov_b64_e32 v[80:81], 0
	v_mov_b64_e32 v[82:83], 0
	v_mov_b64_e32 v[84:85], 0
	v_mov_b64_e32 v[86:87], 0
	v_mov_b64_e32 v[88:89], 0
	v_mov_b64_e32 v[90:91], 0
	v_mov_b64_e32 v[92:93], 0
	v_mov_b64_e32 v[94:95], 0
	v_mov_b64_e32 v[96:97], 0
	v_mov_b64_e32 v[98:99], 0
	v_mov_b64_e32 v[100:101], 0
	v_mov_b64_e32 v[102:103], 0
	v_mov_b64_e32 v[104:105], 0
	v_mov_b64_e32 v[106:107], 0
	v_mov_b64_e32 v[108:109], 0
	v_mov_b64_e32 v[110:111], 0
	v_mov_b64_e32 v[112:113], 0
	v_mov_b64_e32 v[114:115], 0
	v_mov_b64_e32 v[116:117], 0
	v_mov_b64_e32 v[118:119], 0
	v_mov_b64_e32 v[120:121], 0
	v_mov_b64_e32 v[122:123], 0
	v_mov_b64_e32 v[124:125], 0
	v_mov_b64_e32 v[126:127], 0

; template <class Epi, class Sched, bool ALIGN_EPI = false, bool SP2 = false>
; __device__ __forceinline__ void gemm_phase(PG8_LAS unsigned char* lds, const Gemm g, const Sched& S, const Epi& E, int tid_in) {
;     ...
;         for (int t = 0; t < nt; t += 2) {
;             const bool last = (t == nt - 2);
;             const char* a1 = cA + (size_t)(t + 1) * kstep;
;             const char* a2 = last ? nA : cA + (size_t)(t + 2) * kstep; const char* b2 = last ? nB : cB + (size_t)(t + 2) * kstep;
;             const char* a3 = a2 + kstep; const char* b3 = b2 + kstep;
;     ...
; #pragma unroll
;         for (int a = 0; a < 2; ++a)
; #pragma unroll
;             for (int b = 0; b < 2; ++b)
; #pragma unroll
;                 for (int m = 0; m < 4; ++m)
; #pragma unroll
;                     for (int n = 0; n < 2; ++n) acc[a][b][m][n] = (f32x4){0.f, 0.f, 0.f, 0.f};
.Lkeep_acc_5:
	s_add_u32 s38, s38, 0x80
	s_addc_u32 s39, s39, 0
	s_add_u32 s33, s40, 0x100
	s_addc_u32 s80, s41, 0
	s_mov_b32 s40, 0
	v_mov_b64_e32 v[0:1], 0
	v_mov_b64_e32 v[2:3], 0
	v_mov_b64_e32 v[4:5], 0
	v_mov_b64_e32 v[6:7], 0
	v_mov_b64_e32 v[8:9], 0
	v_mov_b64_e32 v[10:11], 0
	v_mov_b64_e32 v[12:13], 0
	v_mov_b64_e32 v[14:15], 0
	v_mov_b64_e32 v[16:17], 0
	v_mov_b64_e32 v[18:19], 0
	v_mov_b64_e32 v[20:21], 0
	v_mov_b64_e32 v[22:23], 0
	v_mov_b64_e32 v[24:25], 0
	v_mov_b64_e32 v[26:27], 0
	v_mov_b64_e32 v[28:29], 0
	v_mov_b64_e32 v[30:31], 0
	v_mov_b64_e32 v[32:33], 0
	v_mov_b64_e32 v[34:35], 0
	v_mov_b64_e32 v[36:37], 0
	v_mov_b64_e32 v[38:39], 0
	v_mov_b64_e32 v[40:41], 0
	v_mov_b64_e32 v[42:43], 0
	v_mov_b64_e32 v[44:45], 0
	v_mov_b64_e32 v[46:47], 0
	v_mov_b64_e32 v[48:49], 0
	v_mov_b64_e32 v[50:51], 0
	v_mov_b64_e32 v[52:53], 0
	v_mov_b64_e32 v[54:55], 0
	v_mov_b64_e32 v[56:57], 0
	v_mov_b64_e32 v[58:59], 0
	v_mov_b64_e32 v[60:61], 0
	v_mov_b64_e32 v[62:63], 0
	v_mov_b64_e32 v[64:65], 0
	v_mov_b64_e32 v[66:67], 0
	v_mov_b64_e32 v[68:69], 0
	v_mov_b64_e32 v[70:71], 0
	v_mov_b64_e32 v[72:73], 0
	v_mov_b64_e32 v[74:75], 0
	v_mov_b64_e32 v[76:77], 0
	v_mov_b64_e32 v[78:79], 0
	v_mov_b64_e32 v[80:81], 0
	v_mov_b64_e32 v[82:83], 0
	v_mov_b64_e32 v[84:85], 0
	v_mov_b64_e32 v[86:87], 0
	v_mov_b64_e32 v[88:89], 0
	v_mov_b64_e32 v[90:91], 0
	v_mov_b64_e32 v[92:93], 0
	v_mov_b64_e32 v[94:95], 0
	v_mov_b64_e32 v[96:97], 0
	v_mov_b64_e32 v[98:99], 0
	v_mov_b64_e32 v[100:101], 0
	v_mov_b64_e32 v[102:103], 0
	v_mov_b64_e32 v[104:105], 0
	v_mov_b64_e32 v[106:107], 0
	v_mov_b64_e32 v[108:109], 0
	v_mov_b64_e32 v[110:111], 0
	v_mov_b64_e32 v[112:113], 0
	v_mov_b64_e32 v[114:115], 0
	v_mov_b64_e32 v[116:117], 0
	v_mov_b64_e32 v[118:119], 0
	v_mov_b64_e32 v[120:121], 0
	v_mov_b64_e32 v[122:123], 0
	v_mov_b64_e32 v[124:125], 0
	v_mov_b64_e32 v[126:127], 0
